# accumulators zeroed between tiles with a few zero-operand MFMAs (C=0) instead of per-register moves, all six GEMM phases
# baseline (speedup 1.0000x reference)
; template <class Epi, class Sched>
; __device__ __forceinline__ void gemm_phase(LAS unsigned char* lds, const int K, const Sched& S, const Epi& E) {
;     ...
; #pragma unroll
;         for (int a = 0; a < 2; ++a)
; #pragma unroll
;             for (int b = 0; b < 2; ++b)
; #pragma unroll
;                 for (int m = 0; m < 4; ++m)
; #pragma unroll
;                     for (int n = 0; n < 2; ++n) acc[a][b][m][n] = (f32x4){0.f, 0.f, 0.f, 0.f};
.LBB0_254:
	s_ashr_i32 s53, s52, 31
	s_lshl_b64 s[54:55], s[52:53], 19
	s_add_u32 s54, s33, s54
	s_addc_u32 s55, s70, s55
	s_and_b64 s[56:57], s[66:67], exec
	s_cselect_b32 s12, s55, s63
	s_cselect_b32 s53, s54, s62
	s_ashr_i32 s51, s50, 31
	s_lshl_b64 s[56:57], s[50:51], 19
	s_add_u32 s56, s10, s56
	s_addc_u32 s57, s11, s57
	s_and_b64 s[66:67], s[66:67], exec
	s_cselect_b32 s51, s57, s65
	s_cselect_b32 s59, s56, s64
	s_add_u32 s62, s62, 0x40080
	s_addc_u32 s63, s63, 0
	s_add_u32 s61, s64, 0x100
	v_mov_b64_e32 v[0:1], 0
	v_mov_b64_e32 v[2:3], 0
	v_mov_b64_e32 v[4:5], 0
	v_mov_b64_e32 v[6:7], 0
	v_mov_b64_e32 v[8:9], 0
	v_mov_b64_e32 v[10:11], 0
	v_mov_b64_e32 v[12:13], 0
	v_mov_b64_e32 v[14:15], 0
	s_addc_u32 s93, s65, 0
	s_mov_b32 s94, -2
	s_waitcnt lgkmcnt(0)
	v_mfma_f32_32x32x16_bf16 v[16:31], v[0:3], v[0:3], 0
	v_mfma_f32_32x32x16_bf16 v[32:47], v[0:3], v[0:3], 0
	v_mfma_f32_32x32x16_bf16 v[48:63], v[0:3], v[0:3], 0
	v_mfma_f32_32x32x16_bf16 v[64:79], v[0:3], v[0:3], 0
	v_mfma_f32_32x32x16_bf16 v[80:95], v[0:3], v[0:3], 0
	v_mfma_f32_32x32x16_bf16 v[96:111], v[0:3], v[0:3], 0
	v_mfma_f32_32x32x16_bf16 v[112:127], v[0:3], v[0:3], 0
	s_cmpk_eq_i32 s58, 0x10
	s_cselect_b32 s101, 1, 0
	s_cmpk_eq_i32 s60, 0x100
	s_cselect_b32 s100, 2, 0
	s_or_b32 s101, s101, s100
	v_readfirstlane_b32 s100, v230
	s_lshr_b32 s100, s100, 5
	s_and_b32 s100, s100, 4
	s_bitcmp1_b32 s101, 0
	s_cselect_b32 s100, s100, 0
	s_or_b32 s101, s101, s100

; template <class Epi, class Sched>
; __device__ __forceinline__ void gemm_phase(LAS unsigned char* lds, const int K, const Sched& S, const Epi& E) {
;     ...
; #pragma unroll
;         for (int a = 0; a < 2; ++a)
; #pragma unroll
;             for (int b = 0; b < 2; ++b)
; #pragma unroll
;                 for (int m = 0; m < 4; ++m)
; #pragma unroll
;                     for (int n = 0; n < 2; ++n) acc[a][b][m][n] = (f32x4){0.f, 0.f, 0.f, 0.f};
.LBB0_735:
	s_ashr_i32 s39, s38, 31
	s_xor_b64 s[40:41], s[48:49], -1
	s_lshl_b64 s[42:43], s[38:39], 18
	s_cmp_eq_u32 s67, 1
	s_cselect_b32 s9, s3, 0x255d9000
	s_cselect_b32 s11, s4, 0x880000
	s_cmp_eq_u32 s67, 2
	s_cselect_b32 s9, 0xb80000, s9
	s_cselect_b32 s39, 0x29619000, s11
	s_add_u32 s9, s14, s9
	s_addc_u32 s11, s15, 0
	s_add_u32 s42, s9, s42
	s_addc_u32 s43, s11, s43
	s_and_b64 s[44:45], s[48:49], exec
	s_cselect_b32 s9, s43, s13
	s_cselect_b32 s11, s42, s12
	s_ashr_i32 s37, s36, 31
	s_lshl_b64 s[44:45], s[36:37], 18
	s_add_u32 s37, s14, s39
	s_addc_u32 s39, s15, 0
	s_add_u32 s44, s37, s44
	s_addc_u32 s45, s39, s45
	s_and_b64 s[48:49], s[48:49], exec
	s_cselect_b32 s37, s45, s47
	s_cselect_b32 s39, s44, s46
	s_add_u32 s12, s12, 0x20080
	s_addc_u32 s13, s13, 0
	s_add_u32 s71, s46, 0x100
	v_mov_b64_e32 v[0:1], 0
	v_mov_b64_e32 v[2:3], 0
	v_mov_b64_e32 v[4:5], 0
	v_mov_b64_e32 v[6:7], 0
	v_mov_b64_e32 v[8:9], 0
	v_mov_b64_e32 v[10:11], 0
	v_mov_b64_e32 v[12:13], 0
	v_mov_b64_e32 v[14:15], 0
	s_addc_u32 s72, s47, 0
	s_mov_b32 s73, -2
	s_waitcnt vmcnt(0)
	v_mfma_f32_32x32x16_bf16 v[16:31], v[0:3], v[0:3], 0
	v_mfma_f32_32x32x16_bf16 v[32:47], v[0:3], v[0:3], 0
	v_mfma_f32_32x32x16_bf16 v[48:63], v[0:3], v[0:3], 0
	v_mfma_f32_32x32x16_bf16 v[64:79], v[0:3], v[0:3], 0
	v_mfma_f32_32x32x16_bf16 v[80:95], v[0:3], v[0:3], 0
	v_mfma_f32_16x16x32_bf16 v[100:103], v[0:3], v[0:3], 0
	v_mfma_f32_16x16x32_bf16 v[104:107], v[0:3], v[0:3], 0
	v_mfma_f32_32x32x16_bf16 v[128:143], v[0:3], v[0:3], 0
	v_mfma_f32_16x16x32_bf16 v[152:155], v[0:3], v[0:3], 0
	v_mfma_f32_16x16x32_bf16 v[156:159], v[0:3], v[0:3], 0

; template <class Epi, class Sched>
; __device__ __forceinline__ void gemm_phase(LAS unsigned char* lds, const int K, const Sched& S, const Epi& E) {
;     ...
;         if (!E.keep_acc(cur))
; #pragma unroll
;         for (int a = 0; a < 2; ++a)
; #pragma unroll
;             for (int b = 0; b < 2; ++b)
; #pragma unroll
;                 for (int m = 0; m < 4; ++m)
; #pragma unroll
;                     for (int n = 0; n < 2; ++n) acc[a][b][m][n] = (f32x4){0.f, 0.f, 0.f, 0.f};
.LBB0_1191:
	s_and_b64 vcc, exec, s[8:9]
	s_cbranch_vccnz .LBB0_1098
	v_mov_b64_e32 v[0:1], 0
	v_mov_b64_e32 v[2:3], 0
	v_mov_b64_e32 v[4:5], 0
	v_mov_b64_e32 v[6:7], 0
	v_mov_b64_e32 v[8:9], 0
	v_mov_b64_e32 v[10:11], 0
	v_mov_b64_e32 v[12:13], 0
	v_mov_b64_e32 v[14:15], 0
	v_mfma_f32_32x32x16_bf16 v[16:31], v[0:3], v[0:3], 0
	v_mfma_f32_32x32x16_bf16 v[32:47], v[0:3], v[0:3], 0
	v_mfma_f32_32x32x16_bf16 v[48:63], v[0:3], v[0:3], 0
	v_mfma_f32_32x32x16_bf16 v[64:79], v[0:3], v[0:3], 0
	v_mfma_f32_32x32x16_bf16 v[80:95], v[0:3], v[0:3], 0
	v_mfma_f32_32x32x16_bf16 v[96:111], v[0:3], v[0:3], 0
	v_mfma_f32_32x32x16_bf16 v[112:127], v[0:3], v[0:3], 0
	s_branch .LBB0_1098

; template <class Epi, class Sched>
; __device__ __forceinline__ void gemm_phase(LAS unsigned char* lds, const int K, const Sched& S, const Epi& E) {
;     ...
; #pragma unroll
;         for (int a = 0; a < 2; ++a)
; #pragma unroll
;             for (int b = 0; b < 2; ++b)
; #pragma unroll
;                 for (int m = 0; m < 4; ++m)
; #pragma unroll
;                     for (int n = 0; n < 2; ++n) acc[a][b][m][n] = (f32x4){0.f, 0.f, 0.f, 0.f};
.LBB0_1279:
	s_ashr_i32 s35, s34, 31
	s_lshl_b64 s[36:37], s[34:35], 19
	s_add_u32 s36, s33, s36
	s_addc_u32 s37, s42, s37
	s_and_b64 s[38:39], s[14:15], exec
	s_cselect_b32 s11, s37, s41
	s_cselect_b32 s13, s36, s40
	s_ashr_i32 s31, s30, 31
	s_lshl_b64 s[38:39], s[30:31], 19
	s_add_u32 s38, s3, s38
	s_addc_u32 s39, s4, s39
	s_and_b64 s[14:15], s[14:15], exec
	s_cselect_b32 s31, s39, s17
	s_cselect_b32 s35, s38, s16
	s_add_u32 s14, s40, 0x40080
	s_addc_u32 s15, s41, 0
	s_add_u32 s56, s16, 0x100
	v_mov_b64_e32 v[0:1], 0
	v_mov_b64_e32 v[2:3], 0
	v_mov_b64_e32 v[4:5], 0
	v_mov_b64_e32 v[6:7], 0
	v_mov_b64_e32 v[8:9], 0
	v_mov_b64_e32 v[10:11], 0
	v_mov_b64_e32 v[12:13], 0
	v_mov_b64_e32 v[14:15], 0
	s_addc_u32 s57, s17, 0
	s_mov_b32 s58, -2
	s_waitcnt lgkmcnt(0)
	v_mfma_f32_32x32x16_bf16 v[16:31], v[0:3], v[0:3], 0
	v_mfma_f32_32x32x16_bf16 v[32:47], v[0:3], v[0:3], 0
	v_mfma_f32_32x32x16_bf16 v[48:63], v[0:3], v[0:3], 0
	v_mfma_f32_32x32x16_bf16 v[64:79], v[0:3], v[0:3], 0
	v_mfma_f32_32x32x16_bf16 v[80:95], v[0:3], v[0:3], 0
	v_mfma_f32_32x32x16_bf16 v[96:111], v[0:3], v[0:3], 0
	v_mfma_f32_32x32x16_bf16 v[112:127], v[0:3], v[0:3], 0
	s_cmpk_eq_i32 s12, 0x100
	s_cselect_b64 vcc, -1, 0

; template <class Epi, class Sched>
; __device__ __forceinline__ void gemm_phase(LAS unsigned char* lds, const int K, const Sched& S, const Epi& E) {
;     ...
; #pragma unroll
;         for (int a = 0; a < 2; ++a)
; #pragma unroll
;             for (int b = 0; b < 2; ++b)
; #pragma unroll
;                 for (int m = 0; m < 4; ++m)
; #pragma unroll
;                     for (int n = 0; n < 2; ++n) acc[a][b][m][n] = (f32x4){0.f, 0.f, 0.f, 0.f};
.LBB0_1370:
	s_ashr_i32 s19, s18, 31
	s_lshl_b64 s[20:21], s[18:19], 19
	s_add_u32 s20, s33, s20
	s_addc_u32 s21, s34, s21
	s_and_b64 s[22:23], s[30:31], exec
	s_cselect_b32 s19, s21, s27
	s_cselect_b32 s44, s20, s26
	s_ashr_i32 s17, s16, 31
	s_lshl_b64 s[22:23], s[16:17], 19
	s_add_u32 s22, s3, s22
	s_addc_u32 s23, s4, s23
	s_and_b64 s[30:31], s[30:31], exec
	s_cselect_b32 s17, s23, s29
	s_cselect_b32 s45, s22, s28
	s_add_u32 s26, s26, 0x40080
	s_addc_u32 s27, s27, 0
	s_add_u32 s46, s28, 0x100
	v_mov_b64_e32 v[0:1], 0
	v_mov_b64_e32 v[2:3], 0
	v_mov_b64_e32 v[4:5], 0
	v_mov_b64_e32 v[6:7], 0
	v_mov_b64_e32 v[8:9], 0
	v_mov_b64_e32 v[10:11], 0
	v_mov_b64_e32 v[12:13], 0
	v_mov_b64_e32 v[14:15], 0
	s_addc_u32 s47, s29, 0
	s_mov_b32 s48, -2
	v_mfma_f32_32x32x16_bf16 v[16:31], v[0:3], v[0:3], 0
	v_mfma_f32_32x32x16_bf16 v[32:47], v[0:3], v[0:3], 0
	v_mfma_f32_32x32x16_bf16 v[48:63], v[0:3], v[0:3], 0
	v_mfma_f32_32x32x16_bf16 v[64:79], v[0:3], v[0:3], 0
	v_mfma_f32_32x32x16_bf16 v[80:95], v[0:3], v[0:3], 0
	v_mfma_f32_32x32x16_bf16 v[96:111], v[0:3], v[0:3], 0
	v_mfma_f32_32x32x16_bf16 v[112:127], v[0:3], v[0:3], 0
	v_lshl_add_u32 v240, s24, 8, v150
	v_ashrrev_i32_e32 v241, 31, v240
	v_lshl_add_u64 v[240:241], v[240:241], 2, s[10:11]
	global_load_dword v232, v[240:241], off
	global_load_dword v233, v[240:241], off offset:64
	global_load_dword v234, v[240:241], off offset:128
	global_load_dword v235, v[240:241], off offset:192
	global_load_dword v236, v[240:241], off offset:512
	global_load_dword v237, v[240:241], off offset:576
	global_load_dword v238, v[240:241], off offset:640
	global_load_dword v239, v[240:241], off offset:704
	s_cmpk_eq_i32 s24, 0x100
	s_cselect_b64 vcc, -1, 0

; template <class Epi, class Sched>
; __device__ __forceinline__ void gemm_phase(LAS unsigned char* lds, const int K, const Sched& S, const Epi& E) {
;     ...
; #pragma unroll
;         for (int a = 0; a < 2; ++a)
; #pragma unroll
;             for (int b = 0; b < 2; ++b)
; #pragma unroll
;                 for (int m = 0; m < 4; ++m)
; #pragma unroll
;                     for (int n = 0; n < 2; ++n) acc[a][b][m][n] = (f32x4){0.f, 0.f, 0.f, 0.f};
.LBB0_1446:
	s_add_u32 s48, s14, 0x100
	v_mov_b64_e32 v[0:1], 0
	v_mov_b64_e32 v[2:3], 0
	v_mov_b64_e32 v[4:5], 0
	v_mov_b64_e32 v[6:7], 0
	v_mov_b64_e32 v[8:9], 0
	v_mov_b64_e32 v[10:11], 0
	v_mov_b64_e32 v[12:13], 0
	v_mov_b64_e32 v[14:15], 0
	s_addc_u32 s49, s15, 0
	s_mov_b32 s50, -2
	s_waitcnt vmcnt(16)
	v_mfma_f32_32x32x16_bf16 v[16:31], v[0:3], v[0:3], 0
	v_mfma_f32_32x32x16_bf16 v[32:47], v[0:3], v[0:3], 0
	v_mfma_f32_32x32x16_bf16 v[48:63], v[0:3], v[0:3], 0
	v_mfma_f32_32x32x16_bf16 v[64:79], v[0:3], v[0:3], 0
	v_mfma_f32_32x32x16_bf16 v[80:95], v[0:3], v[0:3], 0
	v_mfma_f32_32x32x16_bf16 v[96:111], v[0:3], v[0:3], 0
	v_mfma_f32_32x32x16_bf16 v[112:127], v[0:3], v[0:3], 0
	s_cmpk_eq_i32 s47, 0x100
	s_cselect_b64 vcc, -1, 0
